# attention PV section: 37 ds_read_b64 addresses folded into one shared base register plus immediate offsets (36 fewer VALU adds per chunk)
# baseline (speedup 1.0000x reference)
; #define LAS __attribute__((address_space(3)))
; __device__ __forceinline__ unsigned pk2(float lo, float hi) { return f2bf(lo) | (f2bf(hi) << 16); }
; __device__ __forceinline__ void attn_conv_unit(LAS unsigned char* lds, int unit, const bf16* Z, bf16* Y, float* RA,
;                                                const float* qg, const float* kg, const float* sinks, const float* convw) {
;     ...
;             float mx = sink2;
; #pragma unroll
;             for (int a = 0; a < 5; ++a)
; #pragma unroll
;                 for (int r = 0; r < 16; ++r) mx = fmaxf(mx, s[a][r]);
;             mx = fmaxf(mx, __shfl_xor(mx, 32));
;             float l = 0.f;
; #pragma unroll
;             for (int a = 0; a < 5; ++a)
; #pragma unroll
;                 for (int r = 0; r < 16; ++r) { const float p = __builtin_amdgcn_exp2f(s[a][r] - mx); s[a][r] = p; l += p; }
;             l += __shfl_xor(l, 32);
;             l += __builtin_amdgcn_exp2f(sink2 - mx);
;             f32x16 o[2]; o[0] = (f32x16){}; o[1] = (f32x16){};
; #pragma unroll
;             for (int a = 0; a < 5; ++a)
; #pragma unroll
;                 for (int h2 = 0; h2 < 2; ++h2) {
;                     v4u pw; pw.x = pk2(s[a][8 * h2 + 0], s[a][8 * h2 + 1]); pw.y = pk2(s[a][8 * h2 + 2], s[a][8 * h2 + 3]); pw.z = pk2(s[a][8 * h2 + 4], s[a][8 * h2 + 5]); pw.w = pk2(s[a][8 * h2 + 6], s[a][8 * h2 + 7]);
;                     const bf16x8 pf = __builtin_bit_cast(bf16x8, pw);
; #pragma unroll
;                     for (int dt = 0; dt < 2; ++dt) {
;                         const LAS unsigned char* vp = vtb + dt * 32 * VT_STRIDE + (32 * (j + a) + 16 * h2) * 2;
;                         const v2u lo = *(const LAS v2u*)(vp), hi2 = *(const LAS v2u*)(vp + 16);
;                         const v4u vw = (v4u){lo.x, lo.y, hi2.x, hi2.y};
;                         o[dt] = __builtin_amdgcn_mfma_f32_32x32x16_bf16(__builtin_bit_cast(bf16x8, vw), pf, o[dt], 0, 0, 0);
.LBB0_444:
	v_cndmask_b32_e64 v187, v180, v49, s[12:13]
	v_max3_f32 v49, v147, v64, v65
	v_max3_f32 v49, v49, v66, v67
	v_max3_f32 v49, v49, v68, v69
	v_max3_f32 v49, v49, v70, v71
	v_max3_f32 v49, v49, v72, v73
	v_max3_f32 v49, v49, v74, v75
	v_max3_f32 v49, v49, v76, v77
	v_max3_f32 v49, v49, v78, v79
	v_max3_f32 v49, v49, v32, v33
	v_max3_f32 v49, v49, v34, v35
	v_max3_f32 v49, v49, v36, v37
	v_max3_f32 v49, v49, v38, v39
	v_max3_f32 v49, v49, v40, v41
	v_max3_f32 v49, v49, v42, v43
	v_max3_f32 v49, v49, v44, v45
	v_max3_f32 v49, v49, v46, v47
	v_max3_f32 v49, v49, v16, v17
	v_max3_f32 v49, v49, v18, v19
	v_max3_f32 v49, v49, v20, v21
	v_max3_f32 v49, v49, v22, v23
	v_max3_f32 v49, v49, v24, v25
	v_max3_f32 v49, v49, v26, v27
	v_max3_f32 v49, v49, v28, v29
	v_max3_f32 v49, v49, v30, v31
	v_max3_f32 v49, v49, v0, v1
	v_max3_f32 v49, v49, v2, v3
	v_max3_f32 v49, v49, v4, v5
	v_max3_f32 v49, v49, v6, v7
	v_max3_f32 v49, v49, v8, v9
	v_max3_f32 v49, v49, v10, v11
	v_cndmask_b32_e64 v96, v48, v180, s[10:11]
	v_max3_f32 v49, v49, v12, v13
	v_cndmask_b32_e64 v48, v96, v48, s[12:13]
	v_max3_f32 v49, v49, v14, v15
	v_cndmask_b32_e64 v188, v50, v180, s[14:15]
	v_cndmask_b32_e64 v189, v51, v180, s[16:17]
	v_max3_f32 v49, v49, v48, v187
	v_cndmask_b32_e64 v190, v52, v180, s[18:19]
	v_cndmask_b32_e64 v191, v53, v180, s[20:21]
	v_max3_f32 v49, v49, v188, v189
	v_cndmask_b32_e64 v192, v54, v180, s[22:23]
	v_cndmask_b32_e64 v193, v55, v180, s[24:25]
	v_max3_f32 v49, v49, v190, v191
	v_cndmask_b32_e64 v194, v56, v180, s[26:27]
	v_cndmask_b32_e64 v195, v57, v180, s[28:29]
	v_max3_f32 v49, v49, v192, v193
	v_cndmask_b32_e64 v196, v58, v180, s[30:31]
	v_cndmask_b32_e64 v197, v59, v180, s[34:35]
	v_max3_f32 v49, v49, v194, v195
	v_cndmask_b32_e64 v198, v60, v180, s[36:37]
	v_cndmask_b32_e64 v199, v61, v180, s[38:39]
	v_max3_f32 v49, v49, v196, v197
	v_cndmask_b32_e64 v200, v62, v180, s[40:41]
	v_cndmask_b32_e64 v201, v63, v180, s[42:43]
	v_max3_f32 v49, v49, v198, v199
	v_max3_f32 v49, v49, v200, v201
	ds_bpermute_b32 v50, v165, v49
	s_waitcnt lgkmcnt(0)
	v_max_f32_e32 v50, v50, v50
	v_max_f32_e32 v202, v49, v50
	v_sub_f32_e32 v49, v64, v202
	v_sub_f32_e32 v0, v0, v202
	v_exp_f32_e32 v203, v49
	v_sub_f32_e32 v49, v65, v202
	v_exp_f32_e32 v65, v0
	v_sub_f32_e32 v0, v1, v202
	v_exp_f32_e32 v58, v0
	v_sub_f32_e32 v0, v2, v202
	v_exp_f32_e32 v204, v49
	v_sub_f32_e32 v49, v66, v202
	v_exp_f32_e32 v59, v0
	v_sub_f32_e32 v0, v3, v202
	v_exp_f32_e32 v205, v49
	v_sub_f32_e32 v49, v67, v202
	v_exp_f32_e32 v60, v0
	v_sub_f32_e32 v0, v4, v202
	v_exp_f32_e32 v206, v49
	v_sub_f32_e32 v49, v68, v202
	v_exp_f32_e32 v61, v0
	v_sub_f32_e32 v0, v5, v202
	v_exp_f32_e32 v207, v49
	v_sub_f32_e32 v49, v69, v202
	v_exp_f32_e32 v62, v0
	v_sub_f32_e32 v0, v6, v202
	v_exp_f32_e32 v208, v49
	v_sub_f32_e32 v49, v70, v202
	v_exp_f32_e32 v63, v0
	v_sub_f32_e32 v0, v7, v202
	v_exp_f32_e32 v209, v49
	v_sub_f32_e32 v49, v71, v202
	v_sub_f32_e32 v32, v32, v202
	v_exp_f32_e32 v64, v0
	v_sub_f32_e32 v0, v8, v202
	v_exp_f32_e32 v210, v49
	v_sub_f32_e32 v49, v72, v202
	v_exp_f32_e32 v219, v32
	v_sub_f32_e32 v32, v33, v202
	v_exp_f32_e32 v57, v0
	v_sub_f32_e32 v0, v9, v202
	v_exp_f32_e32 v211, v49
	v_sub_f32_e32 v49, v73, v202
	v_exp_f32_e32 v155, v32
	v_sub_f32_e32 v32, v34, v202
	v_exp_f32_e32 v50, v0
	v_sub_f32_e32 v0, v10, v202
	v_exp_f32_e32 v212, v49
	v_sub_f32_e32 v49, v74, v202
	v_exp_f32_e32 v157, v32
	v_sub_f32_e32 v32, v35, v202
	v_exp_f32_e32 v51, v0
	v_sub_f32_e32 v0, v11, v202
	v_exp_f32_e32 v213, v49
	v_sub_f32_e32 v49, v75, v202
	v_exp_f32_e32 v182, v32
	v_sub_f32_e32 v32, v36, v202
	v_exp_f32_e32 v52, v0
	v_sub_f32_e32 v0, v12, v202
	v_exp_f32_e32 v214, v49
	v_sub_f32_e32 v49, v76, v202
	v_exp_f32_e32 v183, v32
	v_sub_f32_e32 v32, v37, v202
	v_exp_f32_e32 v53, v0
	v_sub_f32_e32 v0, v13, v202
	v_exp_f32_e32 v215, v49
	v_sub_f32_e32 v49, v77, v202
	v_exp_f32_e32 v184, v32
	v_sub_f32_e32 v32, v38, v202
	v_exp_f32_e32 v54, v0
	v_sub_f32_e32 v0, v14, v202
	v_exp_f32_e32 v216, v49
	v_sub_f32_e32 v49, v78, v202
	v_exp_f32_e32 v185, v32
	v_sub_f32_e32 v32, v39, v202
	v_exp_f32_e32 v55, v0
	v_sub_f32_e32 v0, v15, v202
	v_exp_f32_e32 v217, v49
	v_sub_f32_e32 v49, v79, v202
	v_exp_f32_e32 v186, v32
	v_sub_f32_e32 v32, v40, v202
	v_exp_f32_e32 v56, v0
	v_sub_f32_e32 v0, v48, v202
	v_exp_f32_e32 v218, v49
	v_exp_f32_e32 v153, v32
	v_sub_f32_e32 v32, v41, v202
	v_exp_f32_e32 v49, v0
	v_sub_f32_e32 v0, v187, v202
	v_exp_f32_e32 v98, v32
	v_sub_f32_e32 v32, v42, v202
	v_exp_f32_e32 v42, v0
	v_sub_f32_e32 v0, v188, v202
	v_exp_f32_e32 v99, v32
	v_sub_f32_e32 v32, v43, v202
	v_exp_f32_e32 v43, v0
	v_sub_f32_e32 v0, v189, v202
	v_exp_f32_e32 v100, v32
	v_sub_f32_e32 v32, v44, v202
	v_exp_f32_e32 v44, v0
	v_sub_f32_e32 v0, v190, v202
	v_exp_f32_e32 v101, v32
	v_sub_f32_e32 v32, v45, v202
	v_exp_f32_e32 v45, v0
	v_sub_f32_e32 v0, v191, v202
	v_exp_f32_e32 v102, v32
	v_sub_f32_e32 v32, v46, v202
	v_exp_f32_e32 v46, v0
	v_sub_f32_e32 v0, v192, v202
	v_exp_f32_e32 v103, v32
	v_sub_f32_e32 v32, v47, v202
	v_sub_f32_e32 v16, v16, v202
	v_exp_f32_e32 v47, v0
	v_sub_f32_e32 v0, v193, v202
	v_exp_f32_e32 v97, v16
	v_sub_f32_e32 v16, v17, v202
	v_exp_f32_e32 v48, v0
	v_sub_f32_e32 v0, v194, v202
	v_exp_f32_e32 v74, v16
	v_sub_f32_e32 v16, v18, v202
	v_exp_f32_e32 v34, v0
	v_sub_f32_e32 v0, v195, v202
	v_exp_f32_e32 v75, v16
	v_sub_f32_e32 v16, v19, v202
	v_exp_f32_e32 v37, v0
	v_sub_f32_e32 v0, v196, v202
	v_exp_f32_e32 v76, v16
	v_sub_f32_e32 v16, v20, v202
	v_exp_f32_e32 v35, v0
	v_sub_f32_e32 v0, v197, v202
	v_exp_f32_e32 v77, v16
	v_sub_f32_e32 v16, v21, v202
	v_exp_f32_e32 v39, v0
	v_sub_f32_e32 v0, v198, v202
	v_exp_f32_e32 v78, v16
	v_sub_f32_e32 v16, v22, v202
	v_exp_f32_e32 v36, v0
	v_sub_f32_e32 v0, v199, v202
	v_exp_f32_e32 v79, v16
	v_sub_f32_e32 v16, v23, v202
	v_exp_f32_e32 v40, v0
	v_sub_f32_e32 v0, v200, v202
	v_exp_f32_e32 v96, v16
	v_sub_f32_e32 v16, v24, v202
	v_exp_f32_e32 v38, v0
	v_sub_f32_e32 v0, v201, v202
	v_exp_f32_e32 v73, v16
	v_sub_f32_e32 v16, v25, v202
	v_exp_f32_e32 v41, v0
	v_sub_f32_e32 v0, v147, v202
	v_add_u32_e32 v33, s3, v145
	v_add_u32_e32 v220, 0x10000, v33
	v_exp_f32_e32 v151, v32
	v_exp_f32_e32 v66, v16
	v_sub_f32_e32 v16, v26, v202
	v_exp_f32_e32 v32, v0
	v_exp_f32_e32 v67, v16
	v_sub_f32_e32 v16, v27, v202
	ds_read_b64 v[0:1], v220 offset:8192
	ds_read_b64 v[2:3], v220 offset:8208
	v_exp_f32_e32 v68, v16
	v_sub_f32_e32 v16, v28, v202
	v_exp_f32_e32 v69, v16
	v_sub_f32_e32 v16, v29, v202
	v_exp_f32_e32 v70, v16
	v_sub_f32_e32 v16, v30, v202
	v_exp_f32_e32 v71, v16
	v_sub_f32_e32 v16, v31, v202
	v_add_f32_e32 v12, 0, v203
	v_cvt_pk_bf16_f32 v7, v209, v210
	v_cvt_pk_bf16_f32 v6, v207, v208
	v_cvt_pk_bf16_f32 v5, v205, v206
	v_cvt_pk_bf16_f32 v4, v203, v204
	v_exp_f32_e32 v72, v16
	s_waitcnt lgkmcnt(0)
; #define LAS __attribute__((address_space(3)))
; __device__ __forceinline__ unsigned pk2(float lo, float hi) { return f2bf(lo) | (f2bf(hi) << 16); }
; __device__ __forceinline__ void attn_conv_unit(LAS unsigned char* lds, int unit, const bf16* Z, bf16* Y, float* RA,
;                                                const float* qg, const float* kg, const float* sinks, const float* convw) {
;     ...
;             float l = 0.f;
; #pragma unroll
;             for (int a = 0; a < 5; ++a)
; #pragma unroll
;                 for (int r = 0; r < 16; ++r) { const float p = __builtin_amdgcn_exp2f(s[a][r] - mx); s[a][r] = p; l += p; }
;             l += __shfl_xor(l, 32);
;             l += __builtin_amdgcn_exp2f(sink2 - mx);
;             f32x16 o[2]; o[0] = (f32x16){}; o[1] = (f32x16){};
; #pragma unroll
;             for (int a = 0; a < 5; ++a)
; #pragma unroll
;                 for (int h2 = 0; h2 < 2; ++h2) {
;                     v4u pw; pw.x = pk2(s[a][8 * h2 + 0], s[a][8 * h2 + 1]); pw.y = pk2(s[a][8 * h2 + 2], s[a][8 * h2 + 3]); pw.z = pk2(s[a][8 * h2 + 4], s[a][8 * h2 + 5]); pw.w = pk2(s[a][8 * h2 + 6], s[a][8 * h2 + 7]);
;                     const bf16x8 pf = __builtin_bit_cast(bf16x8, pw);
; #pragma unroll
;                     for (int dt = 0; dt < 2; ++dt) {
;                         const LAS unsigned char* vp = vtb + dt * 32 * VT_STRIDE + (32 * (j + a) + 16 * h2) * 2;
;                         const v2u lo = *(const LAS v2u*)(vp), hi2 = *(const LAS v2u*)(vp + 16);
;                         const v4u vw = (v4u){lo.x, lo.y, hi2.x, hi2.y};
;                         o[dt] = __builtin_amdgcn_mfma_f32_32x32x16_bf16(__builtin_bit_cast(bf16x8, vw), pf, o[dt], 0, 0, 0);
;                     }
	v_mfma_f32_32x32x16_bf16 v[16:31], v[0:3], v[4:7], 0
	v_add_f32_e32 v0, v204, v12
	v_add_f32_e32 v0, v205, v0
	ds_read_b64 v[8:9], v220 offset:24832
	ds_read_b64 v[10:11], v220 offset:24848
	v_add_f32_e32 v0, v206, v0
	v_add_f32_e32 v0, v207, v0
	v_add_f32_e32 v0, v208, v0
	v_add_f32_e32 v0, v209, v0
	v_add_f32_e32 v187, v210, v0
	s_waitcnt lgkmcnt(0)
	v_mfma_f32_32x32x16_bf16 v[0:15], v[8:11], v[4:7], 0
	v_add_f32_e32 v187, v211, v187
	v_add_f32_e32 v187, v212, v187
	v_cvt_pk_bf16_f32 v194, v215, v216
	v_cvt_pk_bf16_f32 v192, v211, v212
	v_add_f32_e32 v187, v213, v187
	ds_read_b64 v[188:189], v220 offset:8224
	ds_read_b64 v[190:191], v220 offset:8240
	v_cvt_pk_bf16_f32 v195, v217, v218
	v_cvt_pk_bf16_f32 v193, v213, v214
	ds_read_b64 v[196:197], v220 offset:24864
	ds_read_b64 v[198:199], v220 offset:24880
	v_add_f32_e32 v187, v214, v187
	v_add_f32_e32 v187, v215, v187
	v_add_f32_e32 v187, v216, v187
	v_add_f32_e32 v187, v217, v187
	v_add_f32_e32 v187, v218, v187
	s_waitcnt lgkmcnt(2)
	v_mfma_f32_32x32x16_bf16 v[16:31], v[188:191], v[192:195], v[16:31]
	v_add_f32_e32 v187, v219, v187
	s_waitcnt lgkmcnt(0)
	v_mfma_f32_32x32x16_bf16 v[0:15], v[196:199], v[192:195], v[0:15]
	v_cvt_pk_bf16_f32 v192, v219, v155
	v_add_f32_e32 v155, v155, v187
	v_add_f32_e32 v155, v157, v155
	v_add_f32_e32 v155, v182, v155
	ds_read_b64 v[188:189], v220 offset:8256
	ds_read_b64 v[190:191], v220 offset:8272
	v_cvt_pk_bf16_f32 v195, v185, v186
	v_cvt_pk_bf16_f32 v193, v157, v182
	v_add_f32_e32 v155, v183, v155
	v_cvt_pk_bf16_f32 v194, v183, v184
	ds_read_b64 v[196:197], v220 offset:24896
	ds_read_b64 v[198:199], v220 offset:24912
	v_add_f32_e32 v155, v184, v155
	v_add_f32_e32 v155, v185, v155
	v_add_f32_e32 v155, v186, v155
	v_add_f32_e32 v155, v153, v155
	s_waitcnt lgkmcnt(2)
	v_mfma_f32_32x32x16_bf16 v[16:31], v[188:191], v[192:195], v[16:31]
	v_cvt_pk_bf16_f32 v186, v153, v98
	v_add_f32_e32 v98, v98, v155
	s_waitcnt lgkmcnt(0)
	v_mfma_f32_32x32x16_bf16 v[0:15], v[196:199], v[192:195], v[0:15]
	v_add_f32_e32 v98, v99, v98
	v_add_f32_e32 v98, v100, v98
	ds_read_b64 v[182:183], v220 offset:8288
	ds_read_b64 v[184:185], v220 offset:8304
	v_add_u32_e32 v153, 0x16160, v33
	v_add_f32_e32 v98, v101, v98
	v_cvt_pk_bf16_f32 v189, v103, v151
	v_cvt_pk_bf16_f32 v188, v101, v102
	v_cvt_pk_bf16_f32 v187, v99, v100
	v_add_u32_e32 v157, 0x16170, v33
	ds_read_b64 v[190:191], v153
	ds_read_b64 v[192:193], v157
	v_add_f32_e32 v98, v102, v98
	v_add_f32_e32 v98, v103, v98
	v_add_f32_e32 v98, v151, v98
	v_add_f32_e32 v102, v97, v98
	s_waitcnt lgkmcnt(2)
	v_mfma_f32_32x32x16_bf16 v[16:31], v[182:185], v[186:189], v[16:31]
	v_cvt_pk_bf16_f32 v182, v97, v74
	v_add_f32_e32 v74, v74, v102
	s_waitcnt lgkmcnt(0)
	v_mfma_f32_32x32x16_bf16 v[0:15], v[190:193], v[186:189], v[0:15]
	v_add_f32_e32 v74, v75, v74
	v_add_f32_e32 v74, v76, v74
	ds_read_b64 v[98:99], v220 offset:8320
	ds_read_b64 v[100:101], v220 offset:8336
	v_cvt_pk_bf16_f32 v184, v77, v78
	v_cvt_pk_bf16_f32 v183, v75, v76
	v_add_f32_e32 v74, v77, v74
	ds_read_b64 v[186:187], v220 offset:24960
	ds_read_b64 v[188:189], v220 offset:24976
	v_add_f32_e32 v74, v78, v74
	v_add_f32_e32 v74, v79, v74
	v_add_f32_e32 v74, v96, v74
	v_cvt_pk_bf16_f32 v185, v79, v96
	v_add_f32_e32 v78, v73, v74
	s_waitcnt lgkmcnt(2)
	v_mfma_f32_32x32x16_bf16 v[16:31], v[98:101], v[182:185], v[16:31]
	v_cvt_pk_bf16_f32 v96, v73, v66
	v_add_f32_e32 v66, v66, v78
	s_waitcnt lgkmcnt(0)
	v_mfma_f32_32x32x16_bf16 v[0:15], v[186:189], v[182:185], v[0:15]
	v_add_f32_e32 v66, v67, v66
	v_add_f32_e32 v66, v68, v66
	v_cvt_pk_bf16_f32 v99, v71, v72
	v_cvt_pk_bf16_f32 v98, v69, v70
	v_cvt_pk_bf16_f32 v97, v67, v68
	v_add_f32_e32 v66, v69, v66
	ds_read_b64 v[74:75], v220 offset:8352
	ds_read_b64 v[76:77], v220 offset:8368
	v_add_u32_e32 v79, 0x161b0, v33
	ds_read_b64 v[100:101], v220 offset:24992
	ds_read_b64 v[102:103], v79
	v_add_f32_e32 v66, v70, v66
	v_add_f32_e32 v66, v71, v66
	v_add_f32_e32 v66, v72, v66
	v_add_f32_e32 v78, v65, v66
	s_waitcnt lgkmcnt(2)
	v_mfma_f32_32x32x16_bf16 v[16:31], v[74:77], v[96:99], v[16:31]
	v_cvt_pk_bf16_f32 v70, v65, v58
	s_waitcnt lgkmcnt(0)
	v_mfma_f32_32x32x16_bf16 v[0:15], v[100:103], v[96:99], v[0:15]
	v_add_f32_e32 v58, v58, v78
	v_cvt_pk_bf16_f32 v72, v61, v62
	v_add_f32_e32 v58, v59, v58
	ds_read_b64 v[66:67], v220 offset:8384
	ds_read_b64 v[68:69], v220 offset:8400
	v_cvt_pk_bf16_f32 v73, v63, v64
	v_cvt_pk_bf16_f32 v71, v59, v60
	ds_read_b64 v[74:75], v220 offset:25024
	ds_read_b64 v[76:77], v220 offset:25040
	v_add_f32_e32 v58, v60, v58
	v_add_f32_e32 v58, v61, v58
	v_add_f32_e32 v58, v62, v58
	v_add_f32_e32 v58, v63, v58
	v_add_f32_e32 v58, v64, v58
	s_waitcnt lgkmcnt(2)
	v_mfma_f32_32x32x16_bf16 v[16:31], v[66:69], v[70:73], v[16:31]
	v_cvt_pk_bf16_f32 v62, v57, v50
	s_waitcnt lgkmcnt(0)
	v_mfma_f32_32x32x16_bf16 v[0:15], v[74:77], v[70:73], v[0:15]
	v_add_f32_e32 v70, v57, v58
	v_add_f32_e32 v50, v50, v70
	v_cvt_pk_bf16_f32 v65, v55, v56
	v_add_f32_e32 v50, v51, v50
	ds_read_b64 v[58:59], v220 offset:8416
	ds_read_b64 v[60:61], v220 offset:8432
	v_cvt_pk_bf16_f32 v64, v53, v54
	v_cvt_pk_bf16_f32 v63, v51, v52
	ds_read_b64 v[66:67], v220 offset:25056
	ds_read_b64 v[68:69], v220 offset:25072
	v_add_f32_e32 v50, v52, v50
	v_add_f32_e32 v50, v53, v50
	v_add_f32_e32 v50, v54, v50
	v_add_f32_e32 v50, v55, v50
	v_add_f32_e32 v50, v56, v50
	s_waitcnt lgkmcnt(2)
; #define LAS __attribute__((address_space(3)))
; __device__ __forceinline__ unsigned pk2(float lo, float hi) { return f2bf(lo) | (f2bf(hi) << 16); }
; __device__ __forceinline__ void attn_conv_unit(LAS unsigned char* lds, int unit, const bf16* Z, bf16* Y, float* RA,
;                                                const float* qg, const float* kg, const float* sinks, const float* convw) {
;     ...
; #pragma unroll
;             for (int a = 0; a < 5; ++a)
; #pragma unroll
;                 for (int h2 = 0; h2 < 2; ++h2) {
;                     v4u pw; pw.x = pk2(s[a][8 * h2 + 0], s[a][8 * h2 + 1]); pw.y = pk2(s[a][8 * h2 + 2], s[a][8 * h2 + 3]); pw.z = pk2(s[a][8 * h2 + 4], s[a][8 * h2 + 5]); pw.w = pk2(s[a][8 * h2 + 6], s[a][8 * h2 + 7]);
;                     const bf16x8 pf = __builtin_bit_cast(bf16x8, pw);
; #pragma unroll
;                     for (int dt = 0; dt < 2; ++dt) {
;                         const LAS unsigned char* vp = vtb + dt * 32 * VT_STRIDE + (32 * (j + a) + 16 * h2) * 2;
;                         const v2u lo = *(const LAS v2u*)(vp), hi2 = *(const LAS v2u*)(vp + 16);
;                         const v4u vw = (v4u){lo.x, lo.y, hi2.x, hi2.y};
;                         o[dt] = __builtin_amdgcn_mfma_f32_32x32x16_bf16(__builtin_bit_cast(bf16x8, vw), pf, o[dt], 0, 0, 0);
;                     }
;                 }
;             const float inv = 1.0f / l;
;             float sq = 0.f;
; #pragma unroll
;             for (int dt = 0; dt < 2; ++dt)
; #pragma unroll
;                 for (int r = 0; r < 16; ++r) { o[dt][r] *= inv; sq += o[dt][r] * o[dt][r]; }
;             sq += __shfl_xor(sq, 32);
;             if (hi == 0) SS[(32 * j + r32) * 8 + h] = sq;
	v_mfma_f32_32x32x16_bf16 v[16:31], v[58:61], v[62:65], v[16:31]
	v_cvt_pk_bf16_f32 v54, v49, v42
	s_waitcnt lgkmcnt(0)
	v_mfma_f32_32x32x16_bf16 v[0:15], v[66:69], v[62:65], v[0:15]
	v_add_f32_e32 v62, v49, v50
	v_add_f32_e32 v42, v42, v62
	v_add_f32_e32 v42, v43, v42
	v_add_f32_e32 v42, v44, v42
	v_add_f32_e32 v42, v45, v42
	v_add_f32_e32 v42, v46, v42
	v_add_f32_e32 v42, v47, v42
	v_add_f32_e32 v42, v48, v42
	v_add_f32_e32 v42, v34, v42
	v_add_f32_e32 v42, v37, v42
	v_add_f32_e32 v42, v35, v42
	ds_read_b64 v[50:51], v220 offset:8448
	ds_read_b64 v[52:53], v220 offset:8464
	v_add_f32_e32 v42, v39, v42
	v_add_f32_e32 v42, v36, v42
	v_add_f32_e32 v42, v40, v42
	v_add_f32_e32 v42, v38, v42
	v_cvt_pk_bf16_f32 v57, v47, v48
	v_cvt_pk_bf16_f32 v56, v45, v46
	v_cvt_pk_bf16_f32 v55, v43, v44
	v_add_f32_e32 v46, v41, v42
	v_bfe_u32 v45, v37, 16, 1
	s_waitcnt lgkmcnt(0)
	v_mfma_f32_32x32x16_bf16 v[16:31], v[50:53], v[54:57], v[16:31]
	ds_bpermute_b32 v47, v165, v46
	v_add3_u32 v45, v37, v45, s98
	v_cvt_pk_bf16_f32 v40, v36, v40
	v_bfe_u32 v37, v34, 16, 1
	ds_read_b64 v[58:59], v220 offset:25088
	ds_read_b64 v[60:61], v220 offset:25104
	v_cvt_pk_bf16_f32 v39, v35, v39
	v_cvt_pk_bf16_f32 v41, v38, v41
	v_add3_u32 v34, v34, v37, s98
	v_lshrrev_b32_e32 v42, 16, v34
	ds_read_b64 v[34:35], v220 offset:8480
	ds_read_b64 v[36:37], v220 offset:8496
	v_and_or_b32 v38, v45, s96, v42
	ds_read_b64 v[42:43], v220 offset:25120
	ds_read_b64 v[44:45], v220 offset:25136
	s_waitcnt lgkmcnt(6)
	v_add_f32_e32 v33, v46, v47
	s_waitcnt lgkmcnt(4)
	v_mfma_f32_32x32x16_bf16 v[0:15], v[58:61], v[54:57], v[0:15]
	v_add_f32_e32 v32, v32, v33
	v_div_scale_f32 v33, s[48:49], v32, v32, 1.0
	s_waitcnt lgkmcnt(2)
	v_mfma_f32_32x32x16_bf16 v[16:31], v[34:37], v[38:41], v[16:31]
	v_rcp_f32_e32 v34, v33
	s_nop 0
	v_fma_f32 v35, -v33, v34, 1.0
	v_fmac_f32_e32 v34, v35, v34
	v_div_scale_f32 v35, vcc, 1.0, v32, 1.0
	s_waitcnt lgkmcnt(0)
	v_mfma_f32_32x32x16_bf16 v[0:15], v[42:45], v[38:41], v[0:15]
	v_mul_f32_e32 v36, v35, v34
	v_fma_f32 v37, -v33, v36, v35
	v_fmac_f32_e32 v36, v37, v34
	v_fma_f32 v33, -v33, v36, v35
	v_div_fmas_f32 v33, v33, v34, v36
	v_div_fixup_f32 v44, v33, v32, 1.0
	v_mov_b32_e32 v32, v16
	v_mov_b32_e32 v33, v18
	v_mov_b32_e32 v18, v17
	v_mov_b32_e32 v16, v20
	v_mov_b32_e32 v17, v22
	v_pk_mul_f32 v[36:37], v[16:17], v[44:45] op_sel_hi:[1,0]
	v_mov_b32_e32 v16, v24
	v_mov_b32_e32 v17, v26
	v_pk_mul_f32 v[40:41], v[32:33], v[44:45] op_sel_hi:[1,0]
	v_pk_mul_f32 v[32:33], v[16:17], v[44:45] op_sel_hi:[1,0]
	v_mov_b32_e32 v16, v28
	v_mov_b32_e32 v17, v30
	v_mov_b32_e32 v26, v25
	v_pk_mul_f32 v[24:25], v[16:17], v[44:45] op_sel_hi:[1,0]
	v_mov_b32_e32 v16, v0
	v_mov_b32_e32 v17, v2
	v_mov_b32_e32 v2, v1
	v_mov_b32_e32 v0, v4
	v_mov_b32_e32 v1, v6
	v_pk_mul_f32 v[42:43], v[18:19], v[44:45] op_sel_hi:[1,0]
	v_mov_b32_e32 v22, v21
	v_pk_mul_f32 v[20:21], v[16:17], v[44:45] op_sel_hi:[1,0]
	v_pk_mul_f32 v[16:17], v[0:1], v[44:45] op_sel_hi:[1,0]
	v_mov_b32_e32 v0, v8
	v_mov_b32_e32 v1, v10
	v_pk_mul_f32 v[46:47], v[40:41], v[40:41]
	v_pk_mul_f32 v[48:49], v[42:43], v[42:43]
	v_mov_b32_e32 v6, v5
	v_pk_mul_f32 v[4:5], v[0:1], v[44:45] op_sel_hi:[1,0]
	v_mov_b32_e32 v1, v14
	v_mov_b32_e32 v14, v13
	v_pk_mul_f32 v[38:39], v[22:23], v[44:45] op_sel_hi:[1,0]
	v_pk_mul_f32 v[22:23], v[2:3], v[44:45] op_sel_hi:[1,0]
	v_pk_mul_f32 v[2:3], v[14:15], v[44:45] op_sel_hi:[1,0]
	v_add_f32_e32 v14, v46, v48
	v_add_f32_e32 v14, v47, v14
	v_pk_mul_f32 v[50:51], v[36:37], v[36:37]
	v_add_f32_e32 v14, v49, v14
	v_pk_mul_f32 v[52:53], v[38:39], v[38:39]
	v_add_f32_e32 v14, v50, v14
	v_add_f32_e32 v14, v52, v14
	v_add_f32_e32 v14, v51, v14
	v_pk_mul_f32 v[54:55], v[32:33], v[32:33]
	v_pk_mul_f32 v[34:35], v[26:27], v[44:45] op_sel_hi:[1,0]
	v_add_f32_e32 v14, v53, v14
	v_pk_mul_f32 v[56:57], v[34:35], v[34:35]
	v_add_f32_e32 v14, v54, v14
	v_add_f32_e32 v14, v56, v14
	v_mov_b32_e32 v30, v29
	v_add_f32_e32 v14, v55, v14
	v_pk_mul_f32 v[58:59], v[24:25], v[24:25]
	v_pk_mul_f32 v[26:27], v[30:31], v[44:45] op_sel_hi:[1,0]
	v_add_f32_e32 v14, v57, v14
	v_pk_mul_f32 v[28:29], v[26:27], v[26:27]
	v_add_f32_e32 v14, v58, v14
	v_add_f32_e32 v14, v28, v14
	v_add_f32_e32 v14, v59, v14
	v_pk_mul_f32 v[30:31], v[20:21], v[20:21]
	v_add_f32_e32 v14, v29, v14
	v_pk_mul_f32 v[60:61], v[22:23], v[22:23]
	v_add_f32_e32 v14, v30, v14
	v_add_f32_e32 v14, v60, v14
	v_add_f32_e32 v14, v31, v14
	v_pk_mul_f32 v[62:63], v[16:17], v[16:17]
	v_pk_mul_f32 v[18:19], v[6:7], v[44:45] op_sel_hi:[1,0]
	v_add_f32_e32 v14, v61, v14
	v_pk_mul_f32 v[64:65], v[18:19], v[18:19]
	v_add_f32_e32 v14, v62, v14
	v_add_f32_e32 v14, v64, v14
	v_mov_b32_e32 v10, v9
	v_add_f32_e32 v14, v63, v14
	v_pk_mul_f32 v[66:67], v[4:5], v[4:5]
	v_pk_mul_f32 v[6:7], v[10:11], v[44:45] op_sel_hi:[1,0]
	v_add_f32_e32 v14, v65, v14
	v_pk_mul_f32 v[8:9], v[6:7], v[6:7]
	v_add_f32_e32 v14, v66, v14
	v_mov_b32_e32 v0, v12
	v_add_f32_e32 v8, v8, v14
	v_pk_mul_f32 v[0:1], v[0:1], v[44:45] op_sel_hi:[1,0]
	v_add_f32_e32 v8, v67, v8
	v_pk_mul_f32 v[10:11], v[0:1], v[0:1]
	v_add_f32_e32 v8, v9, v8
	v_pk_mul_f32 v[12:13], v[2:3], v[2:3]
	v_add_f32_e32 v8, v10, v8
	v_add_f32_e32 v8, v12, v8
	v_add_f32_e32 v8, v11, v8
	v_add_f32_e32 v8, v13, v8
	ds_bpermute_b32 v9, v165, v8
	s_and_saveexec_b64 s[48:49], s[8:9]
	s_cbranch_execz .LBB0_438
	s_waitcnt lgkmcnt(0)
	v_add_f32_e32 v8, v8, v9
	ds_write_b32 v143, v8
	s_branch .LBB0_438
